# nsa: first K/V tile of pass 2 issued at item start, first window tile issued before top-k (latency hidden behind pass 1 / top-k)
# baseline (speedup 1.0000x reference)
.LBB0_1418:
	s_lshl_b32 s10, s54, 5
	s_and_b32 s10, s10, 0xe0
	s_bfe_u32 s11, s54, 0x50003
	s_or_b32 s11, s10, s11
	s_ashr_i32 s10, s54, 10
	s_bfe_u32 s18, s54, 0x20008
	s_lshl_b32 s13, s10, 2
	s_lshl_b32 s11, s11, 5
	v_mov_b32_e32 v30, v136
	s_and_b32 s12, s54, 0x100
	s_or_b32 s66, s13, s18
	s_xor_b32 s13, s11, 0x1fe0
	s_cmp_eq_u32 s12, 0
	v_ashrrev_i32_e32 v31, 6, v30
	s_cselect_b32 s55, s11, s13
	v_lshlrev_b32_e32 v105, 2, v31
	v_bfe_u32 v104, v30, 2, 2
	v_add_u32_e32 v134, s55, v105
	v_or_b32_e32 v2, v134, v104
	s_ashr_i32 s11, s10, 31
	s_lshl_b64 s[10:11], s[10:11], 13
	v_ashrrev_i32_e32 v3, 31, v2
	s_ashr_i32 s67, s66, 31
	v_and_b32_e32 v49, 3, v30
	s_waitcnt vmcnt(11)
	v_lshl_add_u64 v[84:85], s[10:11], 0, v[2:3]
	s_lshl_b64 s[10:11], s[66:67], 16
	s_lshl_b64 s[12:13], s[66:67], 17
	v_lshlrev_b64 v[4:5], 12, v[84:85]
	v_lshl_or_b32 v32, s18, 2, v49
	s_add_u32 s14, s4, s12
	v_mad_u64_u32 v[6:7], s[16:17], v84, s44, v[116:117]
	v_lshl_add_u64 v[4:5], s[22:23], 0, v[4:5]
	v_lshlrev_b32_e32 v0, 8, v32
	s_addc_u32 s15, s5, s13
	v_mad_i32_i24 v7, v85, s44, v7
	s_lshl_b32 s62, s18, 4
	v_lshl_add_u64 v[4:5], v[4:5], 0, v[0:1]
	v_lshl_add_u64 v[6:7], v[6:7], 0, s[62:63]
	v_lshlrev_b32_e32 v0, 2, v49
	v_lshl_add_u64 v[28:29], v[6:7], 0, v[0:1]
	v_lshlrev_b32_e32 v0, 3, v30
	v_and_b32_e32 v48, 0x78, v0
	v_lshlrev_b32_e32 v0, 1, v48
	v_lshl_add_u64 v[6:7], s[14:15], 0, v[0:1]
	v_add_u32_e32 v0, 0x200, v30
	v_ashrrev_i32_e32 v44, 4, v30
	v_ashrrev_i32_e32 v46, 4, v0
	v_ashrrev_i32_e32 v45, 31, v44
	v_ashrrev_i32_e32 v47, 31, v46
	v_lshlrev_b64 v[100:101], 8, v[44:45]
	v_lshlrev_b64 v[102:103], 8, v[46:47]
	v_and_b32_e32 v124, 48, v30
	v_mov_b32_e32 v125, v1
	v_lshl_add_u64 v[50:51], v[6:7], 0, v[100:101]
	v_lshl_add_u64 v[60:61], v[6:7], 0, v[102:103]
	v_lshl_add_u64 v[16:17], v[4:5], 0, v[124:125]
	global_load_dwordx4 v[20:23], v[50:51], off
	global_load_dwordx4 v[24:27], v[60:61], off
	global_load_dwordx4 v[4:7], v[16:17], off
	global_load_dwordx4 v[8:11], v[16:17], off offset:64
	global_load_dwordx4 v[12:15], v[16:17], off offset:128
	s_nop 0
	global_load_dwordx4 v[16:19], v[16:17], off offset:192
	s_nop 0
	global_load_dword v118, v[28:29], off
	global_load_dword v125, v[28:29], off offset:128
	s_lshl_b64 s[78:79], s[10:11], 1
	s_add_u32 s78, s6, s78
	s_addc_u32 s79, s7, s79
	v_lshlrev_b32_e32 v198, 1, v48
	v_mov_b32_e32 v199, v1
	v_lshl_add_u64 v[198:199], s[78:79], 0, v[198:199]
	v_lshl_add_u64 v[200:201], v[198:199], 0, v[100:101]
	v_lshl_add_u64 v[198:199], v[198:199], 0, v[102:103]
	global_load_dwordx4 v[182:185], v[50:51], off
	global_load_dwordx4 v[186:189], v[200:201], off
	global_load_dwordx4 v[190:193], v[60:61], off
	global_load_dwordx4 v[194:197], v[198:199], off
	v_lshlrev_b32_e32 v0, 4, v30
	v_and_b32_e32 v0, 0xf0, v0
	s_movk_i32 s14, 0x900
	v_add_u32_e32 v138, 16, v0
	v_subrev_u32_e32 v0, 31, v134
	v_subrev_u32_e32 v29, 31, v2
	v_mul_lo_u32 v73, v31, s14
	v_ashrrev_i32_e32 v31, 4, v0
	v_ashrrev_i32_e32 v0, 4, v29
	v_add_u32_e32 v0, 1, v0
	v_cmp_lt_i32_e32 vcc, 30, v2
	v_and_b32_e32 v75, 15, v30
	v_lshrrev_b32_e32 v28, 2, v30
	v_cndmask_b32_e32 v0, 0, v0, vcc
	v_subrev_u32_e32 v29, 63, v31
	v_cmp_lt_i32_e32 vcc, 30, v134
	v_lshl_add_u64 v[68:69], s[12:13], 0, v[100:101]
	v_lshlrev_b32_e32 v126, 4, v75
	s_lshr_b32 s14, s55, 4
	v_cndmask_b32_e32 v108, v119, v29, vcc
	v_and_b32_e32 v57, 12, v28
	v_or_b32_e32 v28, v68, v126
	v_mov_b32_e32 v29, v69
	v_lshl_add_u64 v[70:71], s[12:13], 0, v[102:103]
	v_and_b32_e32 v3, 63, v30
	v_mul_lo_u32 v135, v44, s46
	s_waitcnt vmcnt(16)
	v_add_u32_e32 v98, s39, v73
	v_mul_lo_u32 v139, v46, s46
	s_add_i32 s14, s14, 64
	v_mul_u32_u24_e32 v140, 0x120, v75
	v_lshl_add_u64 v[52:53], s[60:61], 0, v[28:29]
	v_or_b32_e32 v28, v70, v126
	v_mov_b32_e32 v29, v71
	v_bfe_u32 v72, v30, 4, 2
	v_lshlrev_b32_e32 v120, 7, v32
	v_lshl_add_u32 v99, v3, 2, v98
	v_add_u32_e32 v107, v138, v135
	v_add_u32_e32 v106, v138, v139
	v_lshlrev_b64 v[122:123], 11, v[84:85]
	s_lshr_b32 s16, s14, 6
	v_add3_u32 v56, 16, v124, v140
	v_mov_b32_e32 v127, v1
	v_lshl_add_u64 v[54:55], s[60:61], 0, v[28:29]
	s_and_b32 s17, s14, 0xfffffc0
	v_mov_b32_e32 v109, 0xc6ea6000
	s_mov_b32 s18, 1
	s_mov_b32 s19, 0
	v_mov_b32_e32 v74, v1
	ds_write2st64_b32 v99, v121, v121 offset1:1
	ds_write2st64_b32 v99, v121, v121 offset0:2 offset1:3
	ds_write2st64_b32 v99, v121, v121 offset0:4 offset1:5
	ds_write2st64_b32 v99, v121, v121 offset0:6 offset1:7
	s_waitcnt vmcnt(7)
	ds_write_b128 v107, v[20:23]
	s_waitcnt vmcnt(6)
	ds_write_b128 v106, v[24:27]
	s_waitcnt lgkmcnt(0)
	s_barrier
	s_branch .LBB0_1420

.LBB0_1430:
	s_lshl_b64 s[10:11], s[10:11], 1
	s_add_u32 s10, s6, s10
	s_addc_u32 s11, s7, s11
	v_lshlrev_b32_e32 v86, 1, v48
	v_mov_b32_e32 v87, v1
	s_waitcnt vmcnt(1)
	v_lshl_add_u64 v[20:21], s[10:11], 0, v[86:87]
	v_lshl_add_u64 v[22:23], v[20:21], 0, v[100:101]
	v_lshl_add_u64 v[20:21], v[20:21], 0, v[102:103]
	s_nop 0
	v_mov_b32_e32 v48, v74
	s_nop 0
	v_permlane16_swap_b32_e32 v74, v48
	v_lshlrev_b64 v[92:93], 7, v[46:47]
	v_add_f32_e32 v47, v74, v48
	v_mov_b32_e32 v48, v47
	s_nop 1
	v_permlane32_swap_b32_e32 v47, v48
	v_add_f32_e32 v47, v47, v48
	v_div_scale_f32 v48, s[12:13], v47, v47, 1.0
	v_cmp_eq_u32_e64 s[10:11], 0, v49
	v_rcp_f32_e32 v49, v48
	v_lshlrev_b32_e32 v141, 2, v72
	v_lshrrev_b32_e32 v21, 2, v75
	v_or_b32_e32 v46, v141, v21
	v_fma_f32 v50, -v48, v49, 1.0
	v_mul_u32_u24_e32 v143, 0x120, v46
	v_div_scale_f32 v46, vcc, 1.0, v47, 1.0
	v_fmac_f32_e32 v49, v50, v49
	v_mul_f32_e32 v50, v46, v49
	v_fma_f32 v51, -v48, v50, v46
	v_fmac_f32_e32 v50, v51, v49
	v_fma_f32 v46, -v48, v50, v46
	v_div_fmas_f32 v46, v46, v49, v50
	v_div_fixup_f32 v46, v46, v47, 1.0
	v_cmp_lt_f32_e32 vcc, 0, v47
	v_mov_b32_e32 v20, 0
	v_lshlrev_b32_e32 v22, 3, v3
	v_lshl_add_u32 v23, v104, 9, v73
	v_cndmask_b32_e32 v96, 0, v46, vcc
	v_lshlrev_b64 v[88:89], 7, v[44:45]
	s_mov_b32 s18, 0
	v_or_b32_e32 v87, 12, v72
	v_lshl_add_u64 v[90:91], s[52:53], 0, v[68:69]
	v_lshl_add_u64 v[94:95], s[52:53], 0, v[70:71]
	s_mov_b32 s14, 0
	v_and_b32_e32 v142, 24, v22
	v_add3_u32 v110, v23, v141, 16
	v_mov_b32_e32 v21, v20
	v_mov_b32_e32 v22, v20
	v_mov_b32_e32 v23, v20
	s_waitcnt vmcnt(4)
	v_mov_b32_e32 v24, v20
	v_mov_b32_e32 v25, v20
	v_mov_b32_e32 v26, v20
	v_mov_b32_e32 v27, v20
	v_mov_b32_e32 v28, v20
	v_mov_b32_e32 v29, v20
	v_mov_b32_e32 v30, v20
	v_mov_b32_e32 v31, v20
	v_mov_b32_e32 v32, v20
	v_mov_b32_e32 v33, v20
	v_mov_b32_e32 v34, v20
	v_mov_b32_e32 v35, v20
	v_mov_b32_e32 v36, v20
	v_mov_b32_e32 v37, v20
	v_mov_b32_e32 v38, v20
	v_mov_b32_e32 v39, v20
	v_mov_b32_e32 v40, v20
	v_mov_b32_e32 v41, v20
	v_mov_b32_e32 v42, v20
	v_mov_b32_e32 v43, v20
	v_mov_b32_e32 v44, v20
	v_mov_b32_e32 v45, v20
	v_mov_b32_e32 v97, v96
	v_mov_b32_e32 v46, v20
	v_mov_b32_e32 v47, v20
	v_mov_b32_e32 v48, v20
	v_mov_b32_e32 v49, v20
	v_mov_b32_e32 v50, v20
	v_mov_b32_e32 v51, v20
	s_waitcnt vmcnt(0)
	ds_write_b128 v107, v[182:185]
	ds_write_b128 v107, v[186:189] offset:18432
	s_waitcnt vmcnt(1)
	ds_write_b128 v106, v[190:193]
	s_waitcnt vmcnt(0)
	ds_write_b128 v106, v[194:197] offset:18432
	s_waitcnt lgkmcnt(0)
	s_barrier
	s_branch .LBB0_1432

.LBB0_1454:
	s_add_i32 s78, s55, 0xfffffe01
	s_ashr_i32 s78, s78, 6
	s_cmpk_gt_u32 s55, 0x1fe
	s_cselect_b32 s78, s78, 0
	s_ashr_i32 s79, s78, 31
	s_lshl_b64 s[80:81], s[66:67], 21
	s_lshl_b64 s[78:79], s[78:79], 14
	s_add_u32 s82, s8, s80
	s_addc_u32 s83, s9, s81
	s_add_u32 s82, s82, s78
	s_addc_u32 s83, s83, s79
	s_add_u32 s84, s26, s80
	s_addc_u32 s85, s27, s81
	s_add_u32 s84, s84, s78
	s_addc_u32 s85, s85, s79
	v_mov_b32_e32 v198, v86
	v_mov_b32_e32 v199, v1
	v_lshl_add_u64 v[200:201], s[82:83], 0, v[198:199]
	v_lshl_add_u64 v[202:203], s[84:85], 0, v[198:199]
	v_lshlrev_b64 v[204:205], 1, v[88:89]
	v_lshl_add_u64 v[206:207], v[200:201], 0, v[204:205]
	v_lshl_add_u64 v[208:209], v[202:203], 0, v[204:205]
	global_load_dwordx4 v[182:185], v[206:207], off
	global_load_dwordx4 v[186:189], v[208:209], off
	v_lshlrev_b64 v[204:205], 1, v[92:93]
	v_lshl_add_u64 v[206:207], v[200:201], 0, v[204:205]
	v_lshl_add_u64 v[208:209], v[202:203], 0, v[204:205]
	global_load_dwordx4 v[190:193], v[206:207], off
	global_load_dwordx4 v[194:197], v[208:209], off
	s_lshr_b32 s72, s55, 6
	v_cmp_eq_u32_e64 s[12:13], 0, v3
	v_cmp_eq_u32_e32 vcc, s72, v3
	s_add_i32 s16, s72, -1
	v_or_b32_e32 v0, 64, v3
	s_or_b64 s[14:15], s[12:13], vcc
	v_cmp_eq_u32_e32 vcc, s16, v3
	s_add_i32 s16, s72, 0xffffffbf
	s_or_b64 s[14:15], s[14:15], vcc
	v_cmp_eq_u32_e32 vcc, s72, v0
	v_cmp_eq_u32_e64 s[16:17], s16, v3
	s_mov_b32 s73, 0
	s_or_b64 s[16:17], vcc, s[16:17]
	v_cmp_lt_u32_e64 s[18:19], s72, v3
	v_sub_u32_e32 v52, 0x80, v3
	v_mov_b32_e32 v53, v1
	v_cmp_lt_u32_e64 s[20:21], s72, v0
	v_sub_u32_e32 v54, 64, v3
	s_branch .LBB0_1456

.LBB0_1456:
	v_lshl_add_u32 v0, s73, 9, v99
	ds_read2st64_b32 v[56:57], v0 offset1:1
	v_mov_b32_e32 v59, v1
	s_mov_b64 s[68:69], 0
	s_mov_b64 s[70:71], 39
	s_waitcnt lgkmcnt(0)
	v_mov_b32_e32 v0, v56
	v_mov_b32_e32 v58, v57
	v_lshlrev_b64 v[56:57], 7, v[0:1]
	v_lshlrev_b64 v[58:59], 7, v[58:59]
	v_cndmask_b32_e64 v57, v57, 39, s[14:15]
	v_cndmask_b32_e64 v56, v56, v133, s[14:15]
	v_cndmask_b32_e64 v55, v58, v133, s[16:17]
	v_cndmask_b32_e64 v0, v59, 39, s[16:17]
	v_lshl_add_u64 v[56:57], v[56:57], 0, v[52:53]
	v_or_b32_e32 v55, v55, v54
	v_cndmask_b32_e64 v57, v57, 0, s[18:19]
	v_cndmask_b32_e64 v56, v56, 0, s[18:19]
	v_cndmask_b32_e64 v59, v0, 0, s[20:21]
	v_cndmask_b32_e64 v58, v55, 0, s[20:21]
	v_not_b32_e32 v0, 39

.LBB0_1462:
	s_or_b64 exec, exec, s[10:11]
	s_add_i32 s10, s55, 0xfffffe01
	s_ashr_i32 s10, s10, 6
	s_cmpk_gt_u32 s55, 0x1fe
	s_cselect_b32 s10, s10, 0
	s_sub_i32 s14, s72, s10
	s_add_i32 s14, s14, 1
	s_cmp_lt_i32 s14, 1
	s_cbranch_scc1 .LBB0_1416
	s_lshl_b64 s[12:13], s[66:67], 21
	s_add_u32 s15, s8, s12
	s_addc_u32 s21, s9, s13
	s_add_u32 s18, s26, s12
	s_addc_u32 s19, s27, s13
	s_ashr_i32 s11, s10, 31
	s_lshl_b64 s[16:17], s[10:11], 14
	s_add_u32 s18, s18, s16
	s_addc_u32 s19, s19, s17
	s_add_u32 s20, s15, s16
	s_addc_u32 s21, s21, s17
	v_mov_b32_e32 v87, v1
	v_lshl_add_u64 v[52:53], s[20:21], 0, v[86:87]
	v_lshl_add_u64 v[54:55], s[18:19], 0, v[86:87]
	v_lshlrev_b64 v[56:57], 1, v[88:89]
	v_lshl_add_u64 v[58:59], v[52:53], 0, v[56:57]
	v_lshl_add_u64 v[56:57], v[54:55], 0, v[56:57]
	v_lshlrev_b64 v[56:57], 1, v[92:93]
	v_lshl_add_u64 v[52:53], v[52:53], 0, v[56:57]
	v_lshl_add_u64 v[54:55], v[54:55], 0, v[56:57]
	s_lshl_b32 s15, s10, 6
	s_sub_i32 s10, s55, 51
	v_add3_u32 v80, s10, v105, v104
	s_add_u32 s10, s12, s16
	s_addc_u32 s13, s13, s17
	v_sub_u32_e32 v146, v141, v2
	v_mov_b32_e32 v2, v1
	v_mov_b32_e32 v3, v1
	v_sub_u32_e32 v80, v80, v141
	s_add_u32 s12, s52, s10
	v_mov_b32_e32 v0, v1
	v_mov_b64_e32 v[54:55], v[2:3]
	v_mov_b64_e32 v[58:59], v[2:3]
	s_waitcnt vmcnt(5)
	v_mov_b64_e32 v[62:63], v[2:3]
	s_waitcnt vmcnt(4)
	v_mov_b64_e32 v[66:67], v[2:3]
	v_mov_b64_e32 v[70:71], v[2:3]
	v_mov_b64_e32 v[74:75], v[2:3]
	v_mov_b64_e32 v[78:79], v[2:3]
	v_subrev_u32_e32 v147, s15, v80
	s_addc_u32 s13, s53, s13
	v_mov_b64_e32 v[82:83], v[2:3]
	v_add_u32_e32 v145, 0xfffffe04, v134
	s_mov_b32 s11, 0
	v_mov_b32_e32 v148, 0xc6ea6000
	v_mov_b32_e32 v144, 0
	v_mov_b64_e32 v[52:53], v[0:1]
	v_mov_b64_e32 v[56:57], v[0:1]
	v_mov_b64_e32 v[60:61], v[0:1]
	v_mov_b64_e32 v[64:65], v[0:1]
	v_mov_b64_e32 v[68:69], v[0:1]
	v_mov_b64_e32 v[72:73], v[0:1]
	v_mov_b64_e32 v[76:77], v[0:1]
	v_lshl_add_u64 v[128:129], s[12:13], 0, v[100:101]
	v_lshl_add_u64 v[130:131], s[12:13], 0, v[102:103]
	v_mov_b64_e32 v[80:81], v[0:1]
	s_waitcnt vmcnt(0)
	ds_write_b128 v107, v[182:185]
	s_waitcnt vmcnt(2)
	ds_write_b128 v107, v[186:189] offset:18432
	s_waitcnt vmcnt(1)
	ds_write_b128 v106, v[190:193]
	s_waitcnt vmcnt(0)
	ds_write_b128 v106, v[194:197] offset:18432
	s_waitcnt lgkmcnt(0)
	s_barrier
